# sample WGs' deferred grid-barrier check: first poll issued before the sub-barrier L2 write-back and checked after its wait (latency hidden)
# baseline (speedup 1.0000x reference)
.LBB0_213:
	v_lshl_add_u32 v128, s4, 8, v141
	v_ashrrev_i32_e32 v129, 31, v128
	v_lshl_add_u64 v[130:131], v[128:129], 2, s[88:89]
	global_load_dword v136, v[130:131], off
	global_load_dword v236, v[130:131], off offset:64
	global_load_dword v237, v[130:131], off offset:128
	global_load_dword v238, v[130:131], off offset:192
	global_load_dword v239, v[130:131], off offset:512
	global_load_dword v240, v[130:131], off offset:576
	global_load_dword v241, v[130:131], off offset:640
	global_load_dword v242, v[130:131], off offset:704
	v_ashrrev_i32_e32 v129, 1, v140
	s_lshl_b32 s1, s0, 8
	v_readlane_b32 s4, v235, 37
	v_and_b32_e32 v129, -8, v129
	s_or_b32 s1, s4, s1
	v_add_u32_e32 v134, s1, v129
	s_movk_i32 s0, 0x1040
	v_mov_b64_e32 v[132:133], s[52:53]
	v_ashrrev_i32_e32 v135, 31, v134
	v_mad_i64_i32 v[138:139], s[4:5], v128, s0, v[132:133]
	v_or_b32_e32 v140, 16, v128
	v_lshlrev_b64 v[134:135], 1, v[134:135]
	v_ashrrev_i32_e32 v141, 31, v140
	v_lshl_add_u64 v[138:139], v[138:139], 0, v[134:135]
	v_lshl_add_u64 v[142:143], v[140:141], 2, s[88:89]
	s_movk_i32 s1, 0x80
	v_writelane_b32 v235, s1, 45
	s_waitcnt vmcnt(0)
	v_pk_mul_f32 v[126:127], v[126:127], v[136:137] op_sel_hi:[1,0]
	v_pk_mul_f32 v[124:125], v[124:125], v[136:137] op_sel_hi:[1,0]
	v_pk_mul_f32 v[122:123], v[122:123], v[136:137] op_sel_hi:[1,0]
	v_pk_mul_f32 v[120:121], v[120:121], v[136:137] op_sel_hi:[1,0]
	v_pk_mul_f32 v[118:119], v[118:119], v[136:137] op_sel_hi:[1,0]
	v_pk_mul_f32 v[116:117], v[116:117], v[136:137] op_sel_hi:[1,0]
	v_pk_mul_f32 v[144:145], v[114:115], v[136:137] op_sel_hi:[1,0]
	v_pk_mul_f32 v[136:137], v[112:113], v[136:137] op_sel_hi:[1,0]
	v_cvt_pk_bf16_f32 v112, v124, v125
	v_cvt_pk_bf16_f32 v113, v126, v127
	v_cvt_pk_bf16_f32 v114, v120, v121
	v_cvt_pk_bf16_f32 v115, v122, v123
	global_store_dwordx4 v[138:139], v[112:115], off
	s_nop 1
	v_cvt_pk_bf16_f32 v112, v116, v117
	v_cvt_pk_bf16_f32 v113, v118, v119
	v_cvt_pk_bf16_f32 v114, v136, v137
	v_cvt_pk_bf16_f32 v115, v144, v145
	global_store_dwordx4 v[138:139], v[112:115], off offset:256
	s_nop 1
	v_mad_i64_i32 v[116:117], s[4:5], v140, s0, v[132:133]
	v_or_b32_e32 v114, 32, v128
	v_ashrrev_i32_e32 v115, 31, v114
	v_lshl_add_u64 v[116:117], v[116:117], 0, v[134:135]
	v_lshl_add_u64 v[118:119], v[114:115], 2, s[88:89]
	s_nop 1
	v_mov_b32_e32 v112, v236
	v_pk_mul_f32 v[110:111], v[110:111], v[112:113] op_sel_hi:[1,0]
	v_pk_mul_f32 v[108:109], v[108:109], v[112:113] op_sel_hi:[1,0]
	v_pk_mul_f32 v[106:107], v[106:107], v[112:113] op_sel_hi:[1,0]
	v_pk_mul_f32 v[104:105], v[104:105], v[112:113] op_sel_hi:[1,0]
	v_pk_mul_f32 v[102:103], v[102:103], v[112:113] op_sel_hi:[1,0]
	v_pk_mul_f32 v[100:101], v[100:101], v[112:113] op_sel_hi:[1,0]
	v_pk_mul_f32 v[120:121], v[98:99], v[112:113] op_sel_hi:[1,0]
	v_pk_mul_f32 v[112:113], v[96:97], v[112:113] op_sel_hi:[1,0]
	v_cvt_pk_bf16_f32 v96, v108, v109
	v_cvt_pk_bf16_f32 v97, v110, v111
	v_cvt_pk_bf16_f32 v98, v104, v105
	v_cvt_pk_bf16_f32 v99, v106, v107
	global_store_dwordx4 v[116:117], v[96:99], off
	s_nop 1
	v_cvt_pk_bf16_f32 v96, v100, v101
	v_cvt_pk_bf16_f32 v97, v102, v103
	v_cvt_pk_bf16_f32 v98, v112, v113
	v_cvt_pk_bf16_f32 v99, v120, v121
	global_store_dwordx4 v[116:117], v[96:99], off offset:256
	s_nop 1
	v_mad_i64_i32 v[100:101], s[4:5], v114, s0, v[132:133]
	v_or_b32_e32 v98, 48, v128
	v_ashrrev_i32_e32 v99, 31, v98
	v_lshl_add_u64 v[100:101], v[100:101], 0, v[134:135]
	v_lshl_add_u64 v[102:103], v[98:99], 2, s[88:89]
	s_nop 1
	v_mov_b32_e32 v96, v237
	v_pk_mul_f32 v[94:95], v[94:95], v[96:97] op_sel_hi:[1,0]
	v_pk_mul_f32 v[92:93], v[92:93], v[96:97] op_sel_hi:[1,0]
	v_pk_mul_f32 v[90:91], v[90:91], v[96:97] op_sel_hi:[1,0]
	v_pk_mul_f32 v[88:89], v[88:89], v[96:97] op_sel_hi:[1,0]
	v_pk_mul_f32 v[82:83], v[82:83], v[96:97] op_sel_hi:[1,0]
	v_pk_mul_f32 v[80:81], v[80:81], v[96:97] op_sel_hi:[1,0]
	v_pk_mul_f32 v[104:105], v[74:75], v[96:97] op_sel_hi:[1,0]
	v_pk_mul_f32 v[96:97], v[72:73], v[96:97] op_sel_hi:[1,0]
	v_cvt_pk_bf16_f32 v72, v92, v93
	v_cvt_pk_bf16_f32 v73, v94, v95
	v_cvt_pk_bf16_f32 v74, v88, v89
	v_cvt_pk_bf16_f32 v75, v90, v91
	global_store_dwordx4 v[100:101], v[72:75], off
	s_nop 1
	v_cvt_pk_bf16_f32 v72, v80, v81
	v_cvt_pk_bf16_f32 v73, v82, v83
	v_cvt_pk_bf16_f32 v74, v96, v97
	v_cvt_pk_bf16_f32 v75, v104, v105
	global_store_dwordx4 v[100:101], v[72:75], off offset:256
	s_nop 1
	s_nop 1
	v_mov_b32_e32 v72, v238
	v_pk_mul_f32 v[80:81], v[86:87], v[72:73] op_sel_hi:[1,0]
	v_mad_i64_i32 v[74:75], s[4:5], v98, s0, v[132:133]
	v_lshl_add_u64 v[74:75], v[74:75], 0, v[134:135]
	v_pk_mul_f32 v[82:83], v[84:85], v[72:73] op_sel_hi:[1,0]
	v_pk_mul_f32 v[78:79], v[78:79], v[72:73] op_sel_hi:[1,0]
	v_pk_mul_f32 v[76:77], v[76:77], v[72:73] op_sel_hi:[1,0]
	v_pk_mul_f32 v[70:71], v[70:71], v[72:73] op_sel_hi:[1,0]
	v_pk_mul_f32 v[68:69], v[68:69], v[72:73] op_sel_hi:[1,0]
	v_pk_mul_f32 v[84:85], v[66:67], v[72:73] op_sel_hi:[1,0]
	v_pk_mul_f32 v[72:73], v[64:65], v[72:73] op_sel_hi:[1,0]
	v_cvt_pk_bf16_f32 v64, v82, v83
	v_cvt_pk_bf16_f32 v65, v80, v81
	v_cvt_pk_bf16_f32 v66, v76, v77
	v_cvt_pk_bf16_f32 v67, v78, v79
	global_store_dwordx4 v[74:75], v[64:67], off
	s_nop 1
	v_cvt_pk_bf16_f32 v64, v68, v69
	v_cvt_pk_bf16_f32 v65, v70, v71
	v_cvt_pk_bf16_f32 v66, v72, v73
	v_cvt_pk_bf16_f32 v67, v84, v85
	global_store_dwordx4 v[74:75], v[64:67], off offset:256
	s_nop 1
	s_nop 0
	v_add_u32_e32 v65, 0x80, v128
	v_mad_i64_i32 v[66:67], s[4:5], v65, s0, v[132:133]
	v_lshl_add_u64 v[66:67], v[66:67], 0, v[134:135]
	s_nop 1
	v_mov_b32_e32 v64, v239
	v_pk_mul_f32 v[62:63], v[62:63], v[64:65] op_sel_hi:[1,0]
	v_pk_mul_f32 v[60:61], v[60:61], v[64:65] op_sel_hi:[1,0]
	v_pk_mul_f32 v[58:59], v[58:59], v[64:65] op_sel_hi:[1,0]
	v_pk_mul_f32 v[56:57], v[56:57], v[64:65] op_sel_hi:[1,0]
	v_pk_mul_f32 v[54:55], v[54:55], v[64:65] op_sel_hi:[1,0]
	v_pk_mul_f32 v[52:53], v[52:53], v[64:65] op_sel_hi:[1,0]
	v_pk_mul_f32 v[68:69], v[50:51], v[64:65] op_sel_hi:[1,0]
	v_pk_mul_f32 v[64:65], v[48:49], v[64:65] op_sel_hi:[1,0]
	v_cvt_pk_bf16_f32 v48, v60, v61
	v_cvt_pk_bf16_f32 v49, v62, v63
	v_cvt_pk_bf16_f32 v50, v56, v57
	v_cvt_pk_bf16_f32 v51, v58, v59
	global_store_dwordx4 v[66:67], v[48:51], off
	s_nop 1
	v_cvt_pk_bf16_f32 v48, v52, v53
	v_cvt_pk_bf16_f32 v49, v54, v55
	v_cvt_pk_bf16_f32 v50, v64, v65
	v_cvt_pk_bf16_f32 v51, v68, v69
	global_store_dwordx4 v[66:67], v[48:51], off offset:256
	s_nop 1
	s_nop 0
	v_add_u32_e32 v49, 0x90, v128
	v_mad_i64_i32 v[50:51], s[4:5], v49, s0, v[132:133]
	v_lshl_add_u64 v[50:51], v[50:51], 0, v[134:135]
	s_nop 1
	v_mov_b32_e32 v48, v240
	v_pk_mul_f32 v[46:47], v[46:47], v[48:49] op_sel_hi:[1,0]
	v_pk_mul_f32 v[44:45], v[44:45], v[48:49] op_sel_hi:[1,0]
	v_pk_mul_f32 v[42:43], v[42:43], v[48:49] op_sel_hi:[1,0]
	v_pk_mul_f32 v[40:41], v[40:41], v[48:49] op_sel_hi:[1,0]
	v_pk_mul_f32 v[38:39], v[38:39], v[48:49] op_sel_hi:[1,0]
	v_pk_mul_f32 v[36:37], v[36:37], v[48:49] op_sel_hi:[1,0]
	v_pk_mul_f32 v[52:53], v[34:35], v[48:49] op_sel_hi:[1,0]
	v_pk_mul_f32 v[48:49], v[32:33], v[48:49] op_sel_hi:[1,0]
	v_cvt_pk_bf16_f32 v32, v44, v45
	v_cvt_pk_bf16_f32 v33, v46, v47
	v_cvt_pk_bf16_f32 v34, v40, v41
	v_cvt_pk_bf16_f32 v35, v42, v43
	global_store_dwordx4 v[50:51], v[32:35], off
	s_nop 1
	v_cvt_pk_bf16_f32 v32, v36, v37
	v_cvt_pk_bf16_f32 v33, v38, v39
	v_cvt_pk_bf16_f32 v34, v48, v49
	v_cvt_pk_bf16_f32 v35, v52, v53
	global_store_dwordx4 v[50:51], v[32:35], off offset:256
	s_nop 1
	s_nop 0
	v_add_u32_e32 v33, 0xa0, v128
	v_mad_i64_i32 v[34:35], s[4:5], v33, s0, v[132:133]
	v_lshl_add_u64 v[34:35], v[34:35], 0, v[134:135]
	s_nop 1
	v_mov_b32_e32 v32, v241
	v_pk_mul_f32 v[30:31], v[30:31], v[32:33] op_sel_hi:[1,0]
	v_pk_mul_f32 v[28:29], v[28:29], v[32:33] op_sel_hi:[1,0]
	v_pk_mul_f32 v[26:27], v[26:27], v[32:33] op_sel_hi:[1,0]
	v_pk_mul_f32 v[24:25], v[24:25], v[32:33] op_sel_hi:[1,0]
	v_pk_mul_f32 v[22:23], v[22:23], v[32:33] op_sel_hi:[1,0]
	v_pk_mul_f32 v[20:21], v[20:21], v[32:33] op_sel_hi:[1,0]
	v_pk_mul_f32 v[36:37], v[18:19], v[32:33] op_sel_hi:[1,0]
	v_pk_mul_f32 v[32:33], v[16:17], v[32:33] op_sel_hi:[1,0]
	v_cvt_pk_bf16_f32 v16, v28, v29
	v_cvt_pk_bf16_f32 v17, v30, v31
	v_cvt_pk_bf16_f32 v18, v24, v25
	v_cvt_pk_bf16_f32 v19, v26, v27
	global_store_dwordx4 v[34:35], v[16:19], off
	s_nop 1
	v_cvt_pk_bf16_f32 v16, v20, v21
	v_cvt_pk_bf16_f32 v17, v22, v23
	v_cvt_pk_bf16_f32 v18, v32, v33
	v_cvt_pk_bf16_f32 v19, v36, v37
	global_store_dwordx4 v[34:35], v[16:19], off offset:256
	s_nop 1
	s_nop 0
	v_add_u32_e32 v17, 0xb0, v128
	v_mad_i64_i32 v[18:19], s[0:1], v17, s0, v[132:133]
	v_lshl_add_u64 v[18:19], v[18:19], 0, v[134:135]
	v_readlane_b32 s0, v235, 41
	v_readlane_b32 s1, v235, 42
	s_and_b64 vcc, exec, s[0:1]
	s_nop 1
	v_mov_b32_e32 v16, v242
	v_pk_mul_f32 v[14:15], v[14:15], v[16:17] op_sel_hi:[1,0]
	v_pk_mul_f32 v[12:13], v[12:13], v[16:17] op_sel_hi:[1,0]
	v_pk_mul_f32 v[10:11], v[10:11], v[16:17] op_sel_hi:[1,0]
	v_pk_mul_f32 v[8:9], v[8:9], v[16:17] op_sel_hi:[1,0]
	v_pk_mul_f32 v[6:7], v[6:7], v[16:17] op_sel_hi:[1,0]
	v_pk_mul_f32 v[4:5], v[4:5], v[16:17] op_sel_hi:[1,0]
	v_pk_mul_f32 v[20:21], v[2:3], v[16:17] op_sel_hi:[1,0]
	v_pk_mul_f32 v[16:17], v[0:1], v[16:17] op_sel_hi:[1,0]
	v_cvt_pk_bf16_f32 v0, v12, v13
	v_cvt_pk_bf16_f32 v1, v14, v15
	v_cvt_pk_bf16_f32 v2, v8, v9
	v_cvt_pk_bf16_f32 v3, v10, v11
	global_store_dwordx4 v[18:19], v[0:3], off
	s_nop 1
	v_cvt_pk_bf16_f32 v0, v4, v5
	v_cvt_pk_bf16_f32 v1, v6, v7
	v_cvt_pk_bf16_f32 v2, v16, v17
	v_cvt_pk_bf16_f32 v3, v20, v21
	global_store_dwordx4 v[18:19], v[0:3], off offset:256
	s_waitcnt vmcnt(0)
	s_barrier
	s_waitcnt vmcnt(0)
	s_barrier
	s_cbranch_vccnz .LBB0_228
	v_mbcnt_lo_u32_b32 v0, -1, 0
	v_mbcnt_hi_u32_b32 v0, -1, v0
	s_nop 0
	v_cmp_eq_u32_e32 vcc, 0, v0
	s_and_saveexec_b64 s[0:1], vcc
	s_cbranch_execz .LBB0_227
	v_mov_b32_e32 v236, 0x3400
	global_load_dword v237, v236, s[78:79] sc1
	s_mov_b64 s[6:7], exec
	buffer_wbl2 sc1
	s_waitcnt vmcnt(0)
	s_waitcnt vmcnt(0)
	s_movk_i32 s101, 0x4000
	s_branch ATD0_CHECK

ATD0_CHECK:
	v_cmp_le_u32_e32 vcc, s100, v237
	s_cbranch_vccnz ATD0_DONE
	s_sleep 2
	s_add_i32 s101, s101, -1
	s_cmp_eq_u32 s101, 0
	s_cbranch_scc0 ATD0_POLL
ATD0_DONE:
	v_mbcnt_lo_u32_b32 v0, s6, 0
	s_add_u32 s4, s78, 0x3700
	v_mbcnt_hi_u32_b32 v0, s7, v0
	s_addc_u32 s5, s79, 0
	v_cmp_eq_u32_e32 vcc, 0, v0
	s_and_saveexec_b64 s[8:9], vcc
	s_cbranch_execz .LBB0_217
	s_bcnt1_i32_b64 s6, s[6:7]
	v_mov_b32_e32 v0, 0
	v_mov_b32_e32 v1, s6
	global_atomic_add v0, v1, s[4:5]

.LBB0_922:
	v_ashrrev_i32_e32 v128, 1, v140
	v_and_b32_e32 v129, -8, v128
	v_lshl_add_u32 v128, s0, 8, v141
	s_lshl_b32 s0, s4, 8
	v_readlane_b32 s1, v235, 37
	s_or_b32 s0, s1, s0
	v_add_u32_e32 v132, s0, v129
	v_ashrrev_i32_e32 v133, 31, v132
	s_movk_i32 s0, 0x1040
	v_mov_b64_e32 v[130:131], s[52:53]
	v_ashrrev_i32_e32 v129, 31, v128
	v_mad_i64_i32 v[134:135], s[4:5], v128, s0, v[130:131]
	v_lshlrev_b64 v[132:133], 1, v[132:133]
	v_lshl_add_u64 v[136:137], v[134:135], 0, v[132:133]
	v_lshl_add_u64 v[134:135], v[128:129], 2, s[88:89]
	global_load_dword v138, v[134:135], off
	global_load_dword v236, v[134:135], off offset:64
	global_load_dword v237, v[134:135], off offset:128
	global_load_dword v238, v[134:135], off offset:192
	global_load_dword v239, v[134:135], off offset:512
	global_load_dword v240, v[134:135], off offset:576
	global_load_dword v241, v[134:135], off offset:640
	global_load_dword v242, v[134:135], off offset:704
	s_waitcnt vmcnt(0)
	v_pk_mul_f32 v[126:127], v[126:127], v[138:139] op_sel_hi:[1,0]
	v_pk_mul_f32 v[124:125], v[124:125], v[138:139] op_sel_hi:[1,0]
	v_pk_mul_f32 v[140:141], v[122:123], v[138:139] op_sel_hi:[1,0]
	v_pk_mul_f32 v[122:123], v[120:121], v[138:139] op_sel_hi:[1,0]
	v_cvt_pk_bf16_f32 v120, v124, v125
	v_cvt_pk_bf16_f32 v121, v126, v127
	v_pk_mul_f32 v[116:117], v[116:117], v[138:139] op_sel_hi:[1,0]
	v_cvt_pk_bf16_f32 v122, v122, v123
	v_cvt_pk_bf16_f32 v123, v140, v141
	global_store_dwordx4 v[136:137], v[120:123], off
	v_pk_mul_f32 v[118:119], v[118:119], v[138:139] op_sel_hi:[1,0]
	s_nop 0
	v_pk_mul_f32 v[120:121], v[114:115], v[138:139] op_sel_hi:[1,0]
	v_pk_mul_f32 v[114:115], v[112:113], v[138:139] op_sel_hi:[1,0]
	v_cvt_pk_bf16_f32 v112, v116, v117
	v_cvt_pk_bf16_f32 v113, v118, v119
	s_nop 0
	v_cvt_pk_bf16_f32 v114, v114, v115
	v_cvt_pk_bf16_f32 v115, v120, v121
	global_store_dwordx4 v[136:137], v[112:115], off offset:256
	s_nop 1
	v_or_b32_e32 v112, 16, v128
	v_ashrrev_i32_e32 v113, 31, v112
	v_mad_i64_i32 v[114:115], s[4:5], v112, s0, v[130:131]
	v_lshl_add_u64 v[112:113], v[112:113], 2, s[88:89]
	s_nop 1
	v_lshl_add_u64 v[114:115], v[114:115], 0, v[132:133]
	s_nop 1
	v_mov_b32_e32 v112, v236
	v_pk_mul_f32 v[110:111], v[110:111], v[112:113] op_sel_hi:[1,0]
	v_pk_mul_f32 v[108:109], v[108:109], v[112:113] op_sel_hi:[1,0]
	v_pk_mul_f32 v[116:117], v[106:107], v[112:113] op_sel_hi:[1,0]
	v_pk_mul_f32 v[106:107], v[104:105], v[112:113] op_sel_hi:[1,0]
	v_cvt_pk_bf16_f32 v104, v108, v109
	v_cvt_pk_bf16_f32 v105, v110, v111
	v_pk_mul_f32 v[100:101], v[100:101], v[112:113] op_sel_hi:[1,0]
	v_cvt_pk_bf16_f32 v106, v106, v107
	v_cvt_pk_bf16_f32 v107, v116, v117
	global_store_dwordx4 v[114:115], v[104:107], off
	v_pk_mul_f32 v[102:103], v[102:103], v[112:113] op_sel_hi:[1,0]
	s_nop 0
	v_pk_mul_f32 v[104:105], v[98:99], v[112:113] op_sel_hi:[1,0]
	v_pk_mul_f32 v[98:99], v[96:97], v[112:113] op_sel_hi:[1,0]
	v_cvt_pk_bf16_f32 v96, v100, v101
	v_cvt_pk_bf16_f32 v97, v102, v103
	s_nop 0
	v_cvt_pk_bf16_f32 v98, v98, v99
	v_cvt_pk_bf16_f32 v99, v104, v105
	global_store_dwordx4 v[114:115], v[96:99], off offset:256
	s_nop 1
	v_or_b32_e32 v96, 32, v128
	v_ashrrev_i32_e32 v97, 31, v96
	v_mad_i64_i32 v[98:99], s[4:5], v96, s0, v[130:131]
	v_lshl_add_u64 v[96:97], v[96:97], 2, s[88:89]
	s_nop 1
	v_lshl_add_u64 v[98:99], v[98:99], 0, v[132:133]
	s_nop 1
	v_mov_b32_e32 v96, v237
	v_pk_mul_f32 v[94:95], v[94:95], v[96:97] op_sel_hi:[1,0]
	v_pk_mul_f32 v[92:93], v[92:93], v[96:97] op_sel_hi:[1,0]
	v_pk_mul_f32 v[100:101], v[90:91], v[96:97] op_sel_hi:[1,0]
	v_pk_mul_f32 v[90:91], v[88:89], v[96:97] op_sel_hi:[1,0]
	v_cvt_pk_bf16_f32 v88, v92, v93
	v_cvt_pk_bf16_f32 v89, v94, v95
	v_pk_mul_f32 v[84:85], v[84:85], v[96:97] op_sel_hi:[1,0]
	v_cvt_pk_bf16_f32 v90, v90, v91
	v_cvt_pk_bf16_f32 v91, v100, v101
	global_store_dwordx4 v[98:99], v[88:91], off
	v_pk_mul_f32 v[86:87], v[86:87], v[96:97] op_sel_hi:[1,0]
	s_nop 0
	v_pk_mul_f32 v[88:89], v[82:83], v[96:97] op_sel_hi:[1,0]
	v_pk_mul_f32 v[82:83], v[80:81], v[96:97] op_sel_hi:[1,0]
	v_cvt_pk_bf16_f32 v80, v84, v85
	v_cvt_pk_bf16_f32 v81, v86, v87
	s_nop 0
	v_cvt_pk_bf16_f32 v82, v82, v83
	v_cvt_pk_bf16_f32 v83, v88, v89
	global_store_dwordx4 v[98:99], v[80:83], off offset:256
	s_nop 1
	v_or_b32_e32 v80, 48, v128
	v_ashrrev_i32_e32 v81, 31, v80
	v_mad_i64_i32 v[82:83], s[4:5], v80, s0, v[130:131]
	v_lshl_add_u64 v[80:81], v[80:81], 2, s[88:89]
	s_nop 1
	v_lshl_add_u64 v[82:83], v[82:83], 0, v[132:133]
	s_nop 1
	v_mov_b32_e32 v80, v238
	v_pk_mul_f32 v[78:79], v[78:79], v[80:81] op_sel_hi:[1,0]
	v_pk_mul_f32 v[76:77], v[76:77], v[80:81] op_sel_hi:[1,0]
	v_pk_mul_f32 v[84:85], v[74:75], v[80:81] op_sel_hi:[1,0]
	v_pk_mul_f32 v[74:75], v[72:73], v[80:81] op_sel_hi:[1,0]
	v_cvt_pk_bf16_f32 v72, v76, v77
	v_cvt_pk_bf16_f32 v73, v78, v79
	v_pk_mul_f32 v[70:71], v[70:71], v[80:81] op_sel_hi:[1,0]
	v_cvt_pk_bf16_f32 v74, v74, v75
	v_cvt_pk_bf16_f32 v75, v84, v85
	global_store_dwordx4 v[82:83], v[72:75], off
	v_pk_mul_f32 v[68:69], v[68:69], v[80:81] op_sel_hi:[1,0]
	s_nop 0
	v_pk_mul_f32 v[72:73], v[66:67], v[80:81] op_sel_hi:[1,0]
	v_pk_mul_f32 v[66:67], v[64:65], v[80:81] op_sel_hi:[1,0]
	v_cvt_pk_bf16_f32 v64, v68, v69
	v_cvt_pk_bf16_f32 v65, v70, v71
	s_nop 0
	v_cvt_pk_bf16_f32 v66, v66, v67
	v_cvt_pk_bf16_f32 v67, v72, v73
	global_store_dwordx4 v[82:83], v[64:67], off offset:256
	s_nop 1
	s_nop 1
	v_mov_b32_e32 v66, v239
	v_pk_mul_f32 v[62:63], v[62:63], v[66:67] op_sel_hi:[1,0]
	v_add_u32_e32 v64, 0x80, v128
	v_mad_i64_i32 v[64:65], s[4:5], v64, s0, v[130:131]
	v_lshl_add_u64 v[64:65], v[64:65], 0, v[132:133]
	v_pk_mul_f32 v[60:61], v[60:61], v[66:67] op_sel_hi:[1,0]
	v_pk_mul_f32 v[68:69], v[58:59], v[66:67] op_sel_hi:[1,0]
	v_pk_mul_f32 v[58:59], v[56:57], v[66:67] op_sel_hi:[1,0]
	v_cvt_pk_bf16_f32 v56, v60, v61
	v_cvt_pk_bf16_f32 v57, v62, v63
	v_pk_mul_f32 v[54:55], v[54:55], v[66:67] op_sel_hi:[1,0]
	v_cvt_pk_bf16_f32 v58, v58, v59
	v_cvt_pk_bf16_f32 v59, v68, v69
	global_store_dwordx4 v[64:65], v[56:59], off
	v_pk_mul_f32 v[52:53], v[52:53], v[66:67] op_sel_hi:[1,0]
	s_nop 0
	v_pk_mul_f32 v[56:57], v[50:51], v[66:67] op_sel_hi:[1,0]
	v_pk_mul_f32 v[50:51], v[48:49], v[66:67] op_sel_hi:[1,0]
	v_cvt_pk_bf16_f32 v48, v52, v53
	v_cvt_pk_bf16_f32 v49, v54, v55
	s_nop 0
	v_cvt_pk_bf16_f32 v50, v50, v51
	v_cvt_pk_bf16_f32 v51, v56, v57
	global_store_dwordx4 v[64:65], v[48:51], off offset:256
	s_nop 1
	s_nop 1
	v_mov_b32_e32 v50, v240
	v_pk_mul_f32 v[46:47], v[46:47], v[50:51] op_sel_hi:[1,0]
	v_add_u32_e32 v48, 0x90, v128
	v_mad_i64_i32 v[48:49], s[4:5], v48, s0, v[130:131]
	v_lshl_add_u64 v[48:49], v[48:49], 0, v[132:133]
	v_pk_mul_f32 v[44:45], v[44:45], v[50:51] op_sel_hi:[1,0]
	v_pk_mul_f32 v[52:53], v[42:43], v[50:51] op_sel_hi:[1,0]
	v_pk_mul_f32 v[42:43], v[40:41], v[50:51] op_sel_hi:[1,0]
	v_cvt_pk_bf16_f32 v40, v44, v45
	v_cvt_pk_bf16_f32 v41, v46, v47
	v_pk_mul_f32 v[38:39], v[38:39], v[50:51] op_sel_hi:[1,0]
	v_cvt_pk_bf16_f32 v42, v42, v43
	v_cvt_pk_bf16_f32 v43, v52, v53
	global_store_dwordx4 v[48:49], v[40:43], off
	v_pk_mul_f32 v[36:37], v[36:37], v[50:51] op_sel_hi:[1,0]
	s_nop 0
	v_pk_mul_f32 v[40:41], v[34:35], v[50:51] op_sel_hi:[1,0]
	v_pk_mul_f32 v[34:35], v[32:33], v[50:51] op_sel_hi:[1,0]
	v_cvt_pk_bf16_f32 v32, v36, v37
	v_cvt_pk_bf16_f32 v33, v38, v39
	s_nop 0
	v_cvt_pk_bf16_f32 v34, v34, v35
	v_cvt_pk_bf16_f32 v35, v40, v41
	global_store_dwordx4 v[48:49], v[32:35], off offset:256
	s_nop 1
	s_nop 1
	v_mov_b32_e32 v34, v241
	v_pk_mul_f32 v[30:31], v[30:31], v[34:35] op_sel_hi:[1,0]
	v_add_u32_e32 v32, 0xa0, v128
	v_mad_i64_i32 v[32:33], s[4:5], v32, s0, v[130:131]
	v_lshl_add_u64 v[32:33], v[32:33], 0, v[132:133]
	v_pk_mul_f32 v[28:29], v[28:29], v[34:35] op_sel_hi:[1,0]
	v_pk_mul_f32 v[36:37], v[26:27], v[34:35] op_sel_hi:[1,0]
	v_pk_mul_f32 v[26:27], v[24:25], v[34:35] op_sel_hi:[1,0]
	v_cvt_pk_bf16_f32 v24, v28, v29
	v_cvt_pk_bf16_f32 v25, v30, v31
	v_pk_mul_f32 v[22:23], v[22:23], v[34:35] op_sel_hi:[1,0]
	v_cvt_pk_bf16_f32 v26, v26, v27
	v_cvt_pk_bf16_f32 v27, v36, v37
	global_store_dwordx4 v[32:33], v[24:27], off
	v_pk_mul_f32 v[20:21], v[20:21], v[34:35] op_sel_hi:[1,0]
	s_nop 0
	v_pk_mul_f32 v[24:25], v[18:19], v[34:35] op_sel_hi:[1,0]
	v_pk_mul_f32 v[18:19], v[16:17], v[34:35] op_sel_hi:[1,0]
	v_cvt_pk_bf16_f32 v16, v20, v21
	v_cvt_pk_bf16_f32 v17, v22, v23
	s_nop 0
	v_cvt_pk_bf16_f32 v18, v18, v19
	v_cvt_pk_bf16_f32 v19, v24, v25
	global_store_dwordx4 v[32:33], v[16:19], off offset:256
	s_nop 1
	s_nop 1
	v_mov_b32_e32 v18, v242
	v_pk_mul_f32 v[14:15], v[14:15], v[18:19] op_sel_hi:[1,0]
	v_add_u32_e32 v16, 0xb0, v128
	v_mad_i64_i32 v[16:17], s[0:1], v16, s0, v[130:131]
	v_lshl_add_u64 v[16:17], v[16:17], 0, v[132:133]
	v_pk_mul_f32 v[12:13], v[12:13], v[18:19] op_sel_hi:[1,0]
	v_pk_mul_f32 v[20:21], v[10:11], v[18:19] op_sel_hi:[1,0]
	v_pk_mul_f32 v[10:11], v[8:9], v[18:19] op_sel_hi:[1,0]
	v_cvt_pk_bf16_f32 v8, v12, v13
	v_cvt_pk_bf16_f32 v9, v14, v15
	v_pk_mul_f32 v[6:7], v[6:7], v[18:19] op_sel_hi:[1,0]
	v_cvt_pk_bf16_f32 v10, v10, v11
	v_cvt_pk_bf16_f32 v11, v20, v21
	global_store_dwordx4 v[16:17], v[8:11], off
	v_pk_mul_f32 v[4:5], v[4:5], v[18:19] op_sel_hi:[1,0]
	v_readlane_b32 s0, v235, 41
	v_pk_mul_f32 v[8:9], v[2:3], v[18:19] op_sel_hi:[1,0]
	v_pk_mul_f32 v[2:3], v[0:1], v[18:19] op_sel_hi:[1,0]
	v_cvt_pk_bf16_f32 v0, v4, v5
	v_cvt_pk_bf16_f32 v1, v6, v7
	v_readlane_b32 s1, v235, 42
	v_cvt_pk_bf16_f32 v2, v2, v3
	v_cvt_pk_bf16_f32 v3, v8, v9
	global_store_dwordx4 v[16:17], v[0:3], off offset:256
	s_waitcnt vmcnt(0)
	s_barrier
	s_waitcnt vmcnt(0)
	s_and_b64 vcc, exec, s[0:1]
	s_barrier
	s_cbranch_vccnz .LBB0_936
	v_mbcnt_lo_u32_b32 v0, -1, 0
	v_mbcnt_hi_u32_b32 v0, -1, v0
	s_nop 0
	v_cmp_eq_u32_e32 vcc, 0, v0
	s_and_saveexec_b64 s[0:1], vcc
	s_cbranch_execz .LBB0_935
	v_mov_b32_e32 v236, 0x3400
	global_load_dword v237, v236, s[78:79] sc1
	s_mov_b64 s[6:7], exec
	buffer_wbl2 sc1
	s_waitcnt vmcnt(0)
	s_waitcnt vmcnt(0)
	s_movk_i32 s101, 0x4000
	s_branch ATD1_CHECK

ATD1_CHECK:
	v_cmp_le_u32_e32 vcc, s100, v237
	s_cbranch_vccnz ATD1_DONE
	s_sleep 2
	s_add_i32 s101, s101, -1
	s_cmp_eq_u32 s101, 0
	s_cbranch_scc0 ATD1_POLL
ATD1_DONE:
	v_mbcnt_lo_u32_b32 v0, s6, 0
	s_add_u32 s4, s78, 0x3800
	v_mbcnt_hi_u32_b32 v0, s7, v0
	s_addc_u32 s5, s79, 0
	v_cmp_eq_u32_e32 vcc, 0, v0
	s_and_saveexec_b64 s[8:9], vcc
	s_cbranch_execz .LBB0_926
	s_bcnt1_i32_b64 s6, s[6:7]
	v_mov_b32_e32 v0, 0
	v_mov_b32_e32 v1, s6
	global_atomic_add v0, v1, s[4:5]

.LBB0_1631:
	v_ashrrev_i32_e32 v128, 1, v140
	v_and_b32_e32 v129, -8, v128
	v_lshl_add_u32 v128, s0, 8, v141
	s_lshl_b32 s0, s4, 8
	v_readlane_b32 s1, v235, 37
	s_or_b32 s0, s1, s0
	v_add_u32_e32 v132, s0, v129
	v_ashrrev_i32_e32 v133, 31, v132
	s_movk_i32 s0, 0x1040
	v_mov_b64_e32 v[130:131], s[52:53]
	v_ashrrev_i32_e32 v129, 31, v128
	v_mad_i64_i32 v[134:135], s[4:5], v128, s0, v[130:131]
	v_lshlrev_b64 v[132:133], 1, v[132:133]
	v_lshl_add_u64 v[136:137], v[134:135], 0, v[132:133]
	v_lshl_add_u64 v[134:135], v[128:129], 2, s[88:89]
	global_load_dword v138, v[134:135], off
	global_load_dword v236, v[134:135], off offset:64
	global_load_dword v237, v[134:135], off offset:128
	global_load_dword v238, v[134:135], off offset:192
	global_load_dword v239, v[134:135], off offset:512
	global_load_dword v240, v[134:135], off offset:576
	global_load_dword v241, v[134:135], off offset:640
	global_load_dword v242, v[134:135], off offset:704
	s_waitcnt vmcnt(0)
	v_pk_mul_f32 v[126:127], v[126:127], v[138:139] op_sel_hi:[1,0]
	v_pk_mul_f32 v[124:125], v[124:125], v[138:139] op_sel_hi:[1,0]
	v_pk_mul_f32 v[140:141], v[122:123], v[138:139] op_sel_hi:[1,0]
	v_pk_mul_f32 v[122:123], v[120:121], v[138:139] op_sel_hi:[1,0]
	v_cvt_pk_bf16_f32 v120, v124, v125
	v_cvt_pk_bf16_f32 v121, v126, v127
	v_pk_mul_f32 v[116:117], v[116:117], v[138:139] op_sel_hi:[1,0]
	v_cvt_pk_bf16_f32 v122, v122, v123
	v_cvt_pk_bf16_f32 v123, v140, v141
	global_store_dwordx4 v[136:137], v[120:123], off
	v_pk_mul_f32 v[118:119], v[118:119], v[138:139] op_sel_hi:[1,0]
	s_nop 0
	v_pk_mul_f32 v[120:121], v[114:115], v[138:139] op_sel_hi:[1,0]
	v_pk_mul_f32 v[114:115], v[112:113], v[138:139] op_sel_hi:[1,0]
	v_cvt_pk_bf16_f32 v112, v116, v117
	v_cvt_pk_bf16_f32 v113, v118, v119
	s_nop 0
	v_cvt_pk_bf16_f32 v114, v114, v115
	v_cvt_pk_bf16_f32 v115, v120, v121
	global_store_dwordx4 v[136:137], v[112:115], off offset:256
	s_nop 1
	v_or_b32_e32 v112, 16, v128
	v_ashrrev_i32_e32 v113, 31, v112
	v_mad_i64_i32 v[114:115], s[4:5], v112, s0, v[130:131]
	v_lshl_add_u64 v[112:113], v[112:113], 2, s[88:89]
	s_nop 1
	v_lshl_add_u64 v[114:115], v[114:115], 0, v[132:133]
	s_nop 1
	v_mov_b32_e32 v112, v236
	v_pk_mul_f32 v[110:111], v[110:111], v[112:113] op_sel_hi:[1,0]
	v_pk_mul_f32 v[108:109], v[108:109], v[112:113] op_sel_hi:[1,0]
	v_pk_mul_f32 v[116:117], v[106:107], v[112:113] op_sel_hi:[1,0]
	v_pk_mul_f32 v[106:107], v[104:105], v[112:113] op_sel_hi:[1,0]
	v_cvt_pk_bf16_f32 v104, v108, v109
	v_cvt_pk_bf16_f32 v105, v110, v111
	v_pk_mul_f32 v[100:101], v[100:101], v[112:113] op_sel_hi:[1,0]
	v_cvt_pk_bf16_f32 v106, v106, v107
	v_cvt_pk_bf16_f32 v107, v116, v117
	global_store_dwordx4 v[114:115], v[104:107], off
	v_pk_mul_f32 v[102:103], v[102:103], v[112:113] op_sel_hi:[1,0]
	s_nop 0
	v_pk_mul_f32 v[104:105], v[98:99], v[112:113] op_sel_hi:[1,0]
	v_pk_mul_f32 v[98:99], v[96:97], v[112:113] op_sel_hi:[1,0]
	v_cvt_pk_bf16_f32 v96, v100, v101
	v_cvt_pk_bf16_f32 v97, v102, v103
	s_nop 0
	v_cvt_pk_bf16_f32 v98, v98, v99
	v_cvt_pk_bf16_f32 v99, v104, v105
	global_store_dwordx4 v[114:115], v[96:99], off offset:256
	s_nop 1
	v_or_b32_e32 v96, 32, v128
	v_ashrrev_i32_e32 v97, 31, v96
	v_mad_i64_i32 v[98:99], s[4:5], v96, s0, v[130:131]
	v_lshl_add_u64 v[96:97], v[96:97], 2, s[88:89]
	s_nop 1
	v_lshl_add_u64 v[98:99], v[98:99], 0, v[132:133]
	s_nop 1
	v_mov_b32_e32 v96, v237
	v_pk_mul_f32 v[94:95], v[94:95], v[96:97] op_sel_hi:[1,0]
	v_pk_mul_f32 v[92:93], v[92:93], v[96:97] op_sel_hi:[1,0]
	v_pk_mul_f32 v[100:101], v[90:91], v[96:97] op_sel_hi:[1,0]
	v_pk_mul_f32 v[90:91], v[88:89], v[96:97] op_sel_hi:[1,0]
	v_cvt_pk_bf16_f32 v88, v92, v93
	v_cvt_pk_bf16_f32 v89, v94, v95
	v_pk_mul_f32 v[84:85], v[84:85], v[96:97] op_sel_hi:[1,0]
	v_cvt_pk_bf16_f32 v90, v90, v91
	v_cvt_pk_bf16_f32 v91, v100, v101
	global_store_dwordx4 v[98:99], v[88:91], off
	v_pk_mul_f32 v[86:87], v[86:87], v[96:97] op_sel_hi:[1,0]
	s_nop 0
	v_pk_mul_f32 v[88:89], v[82:83], v[96:97] op_sel_hi:[1,0]
	v_pk_mul_f32 v[82:83], v[80:81], v[96:97] op_sel_hi:[1,0]
	v_cvt_pk_bf16_f32 v80, v84, v85
	v_cvt_pk_bf16_f32 v81, v86, v87
	s_nop 0
	v_cvt_pk_bf16_f32 v82, v82, v83
	v_cvt_pk_bf16_f32 v83, v88, v89
	global_store_dwordx4 v[98:99], v[80:83], off offset:256
	s_nop 1
	v_or_b32_e32 v80, 48, v128
	v_ashrrev_i32_e32 v81, 31, v80
	v_mad_i64_i32 v[82:83], s[4:5], v80, s0, v[130:131]
	v_lshl_add_u64 v[80:81], v[80:81], 2, s[88:89]
	s_nop 1
	v_lshl_add_u64 v[82:83], v[82:83], 0, v[132:133]
	s_nop 1
	v_mov_b32_e32 v80, v238
	v_pk_mul_f32 v[78:79], v[78:79], v[80:81] op_sel_hi:[1,0]
	v_pk_mul_f32 v[76:77], v[76:77], v[80:81] op_sel_hi:[1,0]
	v_pk_mul_f32 v[84:85], v[74:75], v[80:81] op_sel_hi:[1,0]
	v_pk_mul_f32 v[74:75], v[72:73], v[80:81] op_sel_hi:[1,0]
	v_cvt_pk_bf16_f32 v72, v76, v77
	v_cvt_pk_bf16_f32 v73, v78, v79
	v_pk_mul_f32 v[70:71], v[70:71], v[80:81] op_sel_hi:[1,0]
	v_cvt_pk_bf16_f32 v74, v74, v75
	v_cvt_pk_bf16_f32 v75, v84, v85
	global_store_dwordx4 v[82:83], v[72:75], off
	v_pk_mul_f32 v[68:69], v[68:69], v[80:81] op_sel_hi:[1,0]
	s_nop 0
	v_pk_mul_f32 v[72:73], v[66:67], v[80:81] op_sel_hi:[1,0]
	v_pk_mul_f32 v[66:67], v[64:65], v[80:81] op_sel_hi:[1,0]
	v_cvt_pk_bf16_f32 v64, v68, v69
	v_cvt_pk_bf16_f32 v65, v70, v71
	s_nop 0
	v_cvt_pk_bf16_f32 v66, v66, v67
	v_cvt_pk_bf16_f32 v67, v72, v73
	global_store_dwordx4 v[82:83], v[64:67], off offset:256
	s_nop 1
	s_nop 1
	v_mov_b32_e32 v66, v239
	v_pk_mul_f32 v[62:63], v[62:63], v[66:67] op_sel_hi:[1,0]
	v_add_u32_e32 v64, 0x80, v128
	v_mad_i64_i32 v[64:65], s[4:5], v64, s0, v[130:131]
	v_lshl_add_u64 v[64:65], v[64:65], 0, v[132:133]
	v_pk_mul_f32 v[60:61], v[60:61], v[66:67] op_sel_hi:[1,0]
	v_pk_mul_f32 v[68:69], v[58:59], v[66:67] op_sel_hi:[1,0]
	v_pk_mul_f32 v[58:59], v[56:57], v[66:67] op_sel_hi:[1,0]
	v_cvt_pk_bf16_f32 v56, v60, v61
	v_cvt_pk_bf16_f32 v57, v62, v63
	v_pk_mul_f32 v[54:55], v[54:55], v[66:67] op_sel_hi:[1,0]
	v_cvt_pk_bf16_f32 v58, v58, v59
	v_cvt_pk_bf16_f32 v59, v68, v69
	global_store_dwordx4 v[64:65], v[56:59], off
	v_pk_mul_f32 v[52:53], v[52:53], v[66:67] op_sel_hi:[1,0]
	s_nop 0
	v_pk_mul_f32 v[56:57], v[50:51], v[66:67] op_sel_hi:[1,0]
	v_pk_mul_f32 v[50:51], v[48:49], v[66:67] op_sel_hi:[1,0]
	v_cvt_pk_bf16_f32 v48, v52, v53
	v_cvt_pk_bf16_f32 v49, v54, v55
	s_nop 0
	v_cvt_pk_bf16_f32 v50, v50, v51
	v_cvt_pk_bf16_f32 v51, v56, v57
	global_store_dwordx4 v[64:65], v[48:51], off offset:256
	s_nop 1
	s_nop 1
	v_mov_b32_e32 v50, v240
	v_pk_mul_f32 v[46:47], v[46:47], v[50:51] op_sel_hi:[1,0]
	v_add_u32_e32 v48, 0x90, v128
	v_mad_i64_i32 v[48:49], s[4:5], v48, s0, v[130:131]
	v_lshl_add_u64 v[48:49], v[48:49], 0, v[132:133]
	v_pk_mul_f32 v[44:45], v[44:45], v[50:51] op_sel_hi:[1,0]
	v_pk_mul_f32 v[52:53], v[42:43], v[50:51] op_sel_hi:[1,0]
	v_pk_mul_f32 v[42:43], v[40:41], v[50:51] op_sel_hi:[1,0]
	v_cvt_pk_bf16_f32 v40, v44, v45
	v_cvt_pk_bf16_f32 v41, v46, v47
	v_pk_mul_f32 v[38:39], v[38:39], v[50:51] op_sel_hi:[1,0]
	v_cvt_pk_bf16_f32 v42, v42, v43
	v_cvt_pk_bf16_f32 v43, v52, v53
	global_store_dwordx4 v[48:49], v[40:43], off
	v_pk_mul_f32 v[36:37], v[36:37], v[50:51] op_sel_hi:[1,0]
	s_nop 0
	v_pk_mul_f32 v[40:41], v[34:35], v[50:51] op_sel_hi:[1,0]
	v_pk_mul_f32 v[34:35], v[32:33], v[50:51] op_sel_hi:[1,0]
	v_cvt_pk_bf16_f32 v32, v36, v37
	v_cvt_pk_bf16_f32 v33, v38, v39
	s_nop 0
	v_cvt_pk_bf16_f32 v34, v34, v35
	v_cvt_pk_bf16_f32 v35, v40, v41
	global_store_dwordx4 v[48:49], v[32:35], off offset:256
	s_nop 1
	s_nop 1
	v_mov_b32_e32 v34, v241
	v_pk_mul_f32 v[30:31], v[30:31], v[34:35] op_sel_hi:[1,0]
	v_add_u32_e32 v32, 0xa0, v128
	v_mad_i64_i32 v[32:33], s[4:5], v32, s0, v[130:131]
	v_lshl_add_u64 v[32:33], v[32:33], 0, v[132:133]
	v_pk_mul_f32 v[28:29], v[28:29], v[34:35] op_sel_hi:[1,0]
	v_pk_mul_f32 v[36:37], v[26:27], v[34:35] op_sel_hi:[1,0]
	v_pk_mul_f32 v[26:27], v[24:25], v[34:35] op_sel_hi:[1,0]
	v_cvt_pk_bf16_f32 v24, v28, v29
	v_cvt_pk_bf16_f32 v25, v30, v31
	v_pk_mul_f32 v[22:23], v[22:23], v[34:35] op_sel_hi:[1,0]
	v_cvt_pk_bf16_f32 v26, v26, v27
	v_cvt_pk_bf16_f32 v27, v36, v37
	global_store_dwordx4 v[32:33], v[24:27], off
	v_pk_mul_f32 v[20:21], v[20:21], v[34:35] op_sel_hi:[1,0]
	s_nop 0
	v_pk_mul_f32 v[24:25], v[18:19], v[34:35] op_sel_hi:[1,0]
	v_pk_mul_f32 v[18:19], v[16:17], v[34:35] op_sel_hi:[1,0]
	v_cvt_pk_bf16_f32 v16, v20, v21
	v_cvt_pk_bf16_f32 v17, v22, v23
	s_nop 0
	v_cvt_pk_bf16_f32 v18, v18, v19
	v_cvt_pk_bf16_f32 v19, v24, v25
	global_store_dwordx4 v[32:33], v[16:19], off offset:256
	s_nop 1
	s_nop 1
	v_mov_b32_e32 v18, v242
	v_pk_mul_f32 v[14:15], v[14:15], v[18:19] op_sel_hi:[1,0]
	v_add_u32_e32 v16, 0xb0, v128
	v_mad_i64_i32 v[16:17], s[0:1], v16, s0, v[130:131]
	v_lshl_add_u64 v[16:17], v[16:17], 0, v[132:133]
	v_pk_mul_f32 v[12:13], v[12:13], v[18:19] op_sel_hi:[1,0]
	v_pk_mul_f32 v[20:21], v[10:11], v[18:19] op_sel_hi:[1,0]
	v_pk_mul_f32 v[10:11], v[8:9], v[18:19] op_sel_hi:[1,0]
	v_cvt_pk_bf16_f32 v8, v12, v13
	v_cvt_pk_bf16_f32 v9, v14, v15
	v_pk_mul_f32 v[6:7], v[6:7], v[18:19] op_sel_hi:[1,0]
	v_cvt_pk_bf16_f32 v10, v10, v11
	v_cvt_pk_bf16_f32 v11, v20, v21
	global_store_dwordx4 v[16:17], v[8:11], off
	v_pk_mul_f32 v[4:5], v[4:5], v[18:19] op_sel_hi:[1,0]
	v_readlane_b32 s0, v235, 41
	v_pk_mul_f32 v[8:9], v[2:3], v[18:19] op_sel_hi:[1,0]
	v_pk_mul_f32 v[2:3], v[0:1], v[18:19] op_sel_hi:[1,0]
	v_cvt_pk_bf16_f32 v0, v4, v5
	v_cvt_pk_bf16_f32 v1, v6, v7
	v_readlane_b32 s1, v235, 42
	v_cvt_pk_bf16_f32 v2, v2, v3
	v_cvt_pk_bf16_f32 v3, v8, v9
	global_store_dwordx4 v[16:17], v[0:3], off offset:256
	s_waitcnt vmcnt(0)
	s_barrier
	s_waitcnt vmcnt(0)
	s_and_b64 vcc, exec, s[0:1]
	s_barrier
	s_cbranch_vccnz .LBB0_1645
	v_mbcnt_lo_u32_b32 v0, -1, 0
	v_mbcnt_hi_u32_b32 v0, -1, v0
	s_nop 0
	v_cmp_eq_u32_e32 vcc, 0, v0
	s_and_saveexec_b64 s[0:1], vcc
	s_cbranch_execz .LBB0_1644
	v_mov_b32_e32 v236, 0x3400
	global_load_dword v237, v236, s[78:79] sc1
	s_mov_b64 s[6:7], exec
	buffer_wbl2 sc1
	s_waitcnt vmcnt(0)
	s_waitcnt vmcnt(0)
	s_movk_i32 s101, 0x4000
	s_branch ATD2_CHECK

ATD2_CHECK:
	v_cmp_le_u32_e32 vcc, s100, v237
	s_cbranch_vccnz ATD2_DONE
	s_sleep 2
	s_add_i32 s101, s101, -1
	s_cmp_eq_u32 s101, 0
	s_cbranch_scc0 ATD2_POLL
ATD2_DONE:
	v_mbcnt_lo_u32_b32 v0, s6, 0
	s_add_u32 s4, s78, 0x3900
	v_mbcnt_hi_u32_b32 v0, s7, v0
	s_addc_u32 s5, s79, 0
	v_cmp_eq_u32_e32 vcc, 0, v0
	s_and_saveexec_b64 s[8:9], vcc
	s_cbranch_execz .LBB0_1635
	s_bcnt1_i32_b64 s6, s[6:7]
	v_mov_b32_e32 v0, 0
	v_mov_b32_e32 v1, s6
	global_atomic_add v0, v1, s[4:5]

.LBB0_2340:
	v_lshl_add_u32 v128, s4, 8, v141
	v_ashrrev_i32_e32 v129, 31, v128
	v_lshl_add_u64 v[130:131], v[128:129], 2, s[88:89]
	global_load_dword v136, v[130:131], off
	global_load_dword v236, v[130:131], off offset:64
	global_load_dword v237, v[130:131], off offset:128
	global_load_dword v238, v[130:131], off offset:192
	global_load_dword v239, v[130:131], off offset:512
	global_load_dword v240, v[130:131], off offset:576
	global_load_dword v241, v[130:131], off offset:640
	global_load_dword v242, v[130:131], off offset:704
	v_ashrrev_i32_e32 v129, 1, v140
	s_lshl_b32 s1, s0, 8
	v_readlane_b32 s4, v235, 37
	v_and_b32_e32 v129, -8, v129
	s_or_b32 s1, s4, s1
	v_add_u32_e32 v134, s1, v129
	s_movk_i32 s0, 0x1040
	v_mov_b64_e32 v[132:133], s[52:53]
	v_ashrrev_i32_e32 v135, 31, v134
	v_mad_i64_i32 v[138:139], s[4:5], v128, s0, v[132:133]
	v_or_b32_e32 v140, 16, v128
	v_lshlrev_b64 v[134:135], 1, v[134:135]
	v_ashrrev_i32_e32 v141, 31, v140
	v_lshl_add_u64 v[138:139], v[138:139], 0, v[134:135]
	v_lshl_add_u64 v[142:143], v[140:141], 2, s[88:89]
	s_waitcnt vmcnt(0)
	v_pk_mul_f32 v[126:127], v[126:127], v[136:137] op_sel_hi:[1,0]
	v_pk_mul_f32 v[124:125], v[124:125], v[136:137] op_sel_hi:[1,0]
	v_pk_mul_f32 v[122:123], v[122:123], v[136:137] op_sel_hi:[1,0]
	v_pk_mul_f32 v[120:121], v[120:121], v[136:137] op_sel_hi:[1,0]
	v_pk_mul_f32 v[118:119], v[118:119], v[136:137] op_sel_hi:[1,0]
	v_pk_mul_f32 v[116:117], v[116:117], v[136:137] op_sel_hi:[1,0]
	v_pk_mul_f32 v[144:145], v[114:115], v[136:137] op_sel_hi:[1,0]
	v_pk_mul_f32 v[136:137], v[112:113], v[136:137] op_sel_hi:[1,0]
	v_cvt_pk_bf16_f32 v112, v124, v125
	v_cvt_pk_bf16_f32 v113, v126, v127
	v_cvt_pk_bf16_f32 v114, v120, v121
	v_cvt_pk_bf16_f32 v115, v122, v123
	global_store_dwordx4 v[138:139], v[112:115], off
	s_nop 1
	v_cvt_pk_bf16_f32 v112, v116, v117
	v_cvt_pk_bf16_f32 v113, v118, v119
	v_cvt_pk_bf16_f32 v114, v136, v137
	v_cvt_pk_bf16_f32 v115, v144, v145
	global_store_dwordx4 v[138:139], v[112:115], off offset:256
	s_nop 1
	v_mad_i64_i32 v[116:117], s[4:5], v140, s0, v[132:133]
	v_or_b32_e32 v114, 32, v128
	v_ashrrev_i32_e32 v115, 31, v114
	v_lshl_add_u64 v[116:117], v[116:117], 0, v[134:135]
	v_lshl_add_u64 v[118:119], v[114:115], 2, s[88:89]
	s_nop 1
	v_mov_b32_e32 v112, v236
	v_pk_mul_f32 v[110:111], v[110:111], v[112:113] op_sel_hi:[1,0]
	v_pk_mul_f32 v[108:109], v[108:109], v[112:113] op_sel_hi:[1,0]
	v_pk_mul_f32 v[106:107], v[106:107], v[112:113] op_sel_hi:[1,0]
	v_pk_mul_f32 v[104:105], v[104:105], v[112:113] op_sel_hi:[1,0]
	v_pk_mul_f32 v[102:103], v[102:103], v[112:113] op_sel_hi:[1,0]
	v_pk_mul_f32 v[100:101], v[100:101], v[112:113] op_sel_hi:[1,0]
	v_pk_mul_f32 v[120:121], v[98:99], v[112:113] op_sel_hi:[1,0]
	v_pk_mul_f32 v[112:113], v[96:97], v[112:113] op_sel_hi:[1,0]
	v_cvt_pk_bf16_f32 v96, v108, v109
	v_cvt_pk_bf16_f32 v97, v110, v111
	v_cvt_pk_bf16_f32 v98, v104, v105
	v_cvt_pk_bf16_f32 v99, v106, v107
	global_store_dwordx4 v[116:117], v[96:99], off
	s_nop 1
	v_cvt_pk_bf16_f32 v96, v100, v101
	v_cvt_pk_bf16_f32 v97, v102, v103
	v_cvt_pk_bf16_f32 v98, v112, v113
	v_cvt_pk_bf16_f32 v99, v120, v121
	global_store_dwordx4 v[116:117], v[96:99], off offset:256
	s_nop 1
	v_mad_i64_i32 v[100:101], s[4:5], v114, s0, v[132:133]
	v_or_b32_e32 v98, 48, v128
	v_ashrrev_i32_e32 v99, 31, v98
	v_lshl_add_u64 v[100:101], v[100:101], 0, v[134:135]
	v_lshl_add_u64 v[102:103], v[98:99], 2, s[88:89]
	s_nop 1
	v_mov_b32_e32 v96, v237
	v_pk_mul_f32 v[94:95], v[94:95], v[96:97] op_sel_hi:[1,0]
	v_pk_mul_f32 v[92:93], v[92:93], v[96:97] op_sel_hi:[1,0]
	v_pk_mul_f32 v[90:91], v[90:91], v[96:97] op_sel_hi:[1,0]
	v_pk_mul_f32 v[88:89], v[88:89], v[96:97] op_sel_hi:[1,0]
	v_pk_mul_f32 v[82:83], v[82:83], v[96:97] op_sel_hi:[1,0]
	v_pk_mul_f32 v[80:81], v[80:81], v[96:97] op_sel_hi:[1,0]
	v_pk_mul_f32 v[104:105], v[74:75], v[96:97] op_sel_hi:[1,0]
	v_pk_mul_f32 v[96:97], v[72:73], v[96:97] op_sel_hi:[1,0]
	v_cvt_pk_bf16_f32 v72, v92, v93
	v_cvt_pk_bf16_f32 v73, v94, v95
	v_cvt_pk_bf16_f32 v74, v88, v89
	v_cvt_pk_bf16_f32 v75, v90, v91
	global_store_dwordx4 v[100:101], v[72:75], off
	s_nop 1
	v_cvt_pk_bf16_f32 v72, v80, v81
	v_cvt_pk_bf16_f32 v73, v82, v83
	v_cvt_pk_bf16_f32 v74, v96, v97
	v_cvt_pk_bf16_f32 v75, v104, v105
	global_store_dwordx4 v[100:101], v[72:75], off offset:256
	s_nop 1
	s_nop 1
	v_mov_b32_e32 v72, v238
	v_pk_mul_f32 v[80:81], v[86:87], v[72:73] op_sel_hi:[1,0]
	v_mad_i64_i32 v[74:75], s[4:5], v98, s0, v[132:133]
	v_lshl_add_u64 v[74:75], v[74:75], 0, v[134:135]
	v_pk_mul_f32 v[82:83], v[84:85], v[72:73] op_sel_hi:[1,0]
	v_pk_mul_f32 v[78:79], v[78:79], v[72:73] op_sel_hi:[1,0]
	v_pk_mul_f32 v[76:77], v[76:77], v[72:73] op_sel_hi:[1,0]
	v_pk_mul_f32 v[70:71], v[70:71], v[72:73] op_sel_hi:[1,0]
	v_pk_mul_f32 v[68:69], v[68:69], v[72:73] op_sel_hi:[1,0]
	v_pk_mul_f32 v[84:85], v[66:67], v[72:73] op_sel_hi:[1,0]
	v_pk_mul_f32 v[72:73], v[64:65], v[72:73] op_sel_hi:[1,0]
	v_cvt_pk_bf16_f32 v64, v82, v83
	v_cvt_pk_bf16_f32 v65, v80, v81
	v_cvt_pk_bf16_f32 v66, v76, v77
	v_cvt_pk_bf16_f32 v67, v78, v79
	global_store_dwordx4 v[74:75], v[64:67], off
	s_nop 1
	v_cvt_pk_bf16_f32 v64, v68, v69
	v_cvt_pk_bf16_f32 v65, v70, v71
	v_cvt_pk_bf16_f32 v66, v72, v73
	v_cvt_pk_bf16_f32 v67, v84, v85
	global_store_dwordx4 v[74:75], v[64:67], off offset:256
	s_nop 1
	s_nop 0
	v_add_u32_e32 v65, 0x80, v128
	v_mad_i64_i32 v[66:67], s[4:5], v65, s0, v[132:133]
	v_lshl_add_u64 v[66:67], v[66:67], 0, v[134:135]
	s_nop 1
	v_mov_b32_e32 v64, v239
	v_pk_mul_f32 v[62:63], v[62:63], v[64:65] op_sel_hi:[1,0]
	v_pk_mul_f32 v[60:61], v[60:61], v[64:65] op_sel_hi:[1,0]
	v_pk_mul_f32 v[58:59], v[58:59], v[64:65] op_sel_hi:[1,0]
	v_pk_mul_f32 v[56:57], v[56:57], v[64:65] op_sel_hi:[1,0]
	v_pk_mul_f32 v[54:55], v[54:55], v[64:65] op_sel_hi:[1,0]
	v_pk_mul_f32 v[52:53], v[52:53], v[64:65] op_sel_hi:[1,0]
	v_pk_mul_f32 v[68:69], v[50:51], v[64:65] op_sel_hi:[1,0]
	v_pk_mul_f32 v[64:65], v[48:49], v[64:65] op_sel_hi:[1,0]
	v_cvt_pk_bf16_f32 v48, v60, v61
	v_cvt_pk_bf16_f32 v49, v62, v63
	v_cvt_pk_bf16_f32 v50, v56, v57
	v_cvt_pk_bf16_f32 v51, v58, v59
	global_store_dwordx4 v[66:67], v[48:51], off
	s_nop 1
	v_cvt_pk_bf16_f32 v48, v52, v53
	v_cvt_pk_bf16_f32 v49, v54, v55
	v_cvt_pk_bf16_f32 v50, v64, v65
	v_cvt_pk_bf16_f32 v51, v68, v69
	global_store_dwordx4 v[66:67], v[48:51], off offset:256
	s_nop 1
	s_nop 0
	v_add_u32_e32 v49, 0x90, v128
	v_mad_i64_i32 v[50:51], s[4:5], v49, s0, v[132:133]
	v_lshl_add_u64 v[50:51], v[50:51], 0, v[134:135]
	s_nop 1
	v_mov_b32_e32 v48, v240
	v_pk_mul_f32 v[46:47], v[46:47], v[48:49] op_sel_hi:[1,0]
	v_pk_mul_f32 v[44:45], v[44:45], v[48:49] op_sel_hi:[1,0]
	v_pk_mul_f32 v[42:43], v[42:43], v[48:49] op_sel_hi:[1,0]
	v_pk_mul_f32 v[40:41], v[40:41], v[48:49] op_sel_hi:[1,0]
	v_pk_mul_f32 v[38:39], v[38:39], v[48:49] op_sel_hi:[1,0]
	v_pk_mul_f32 v[36:37], v[36:37], v[48:49] op_sel_hi:[1,0]
	v_pk_mul_f32 v[52:53], v[34:35], v[48:49] op_sel_hi:[1,0]
	v_pk_mul_f32 v[48:49], v[32:33], v[48:49] op_sel_hi:[1,0]
	v_cvt_pk_bf16_f32 v32, v44, v45
	v_cvt_pk_bf16_f32 v33, v46, v47
	v_cvt_pk_bf16_f32 v34, v40, v41
	v_cvt_pk_bf16_f32 v35, v42, v43
	global_store_dwordx4 v[50:51], v[32:35], off
	s_nop 1
	v_cvt_pk_bf16_f32 v32, v36, v37
	v_cvt_pk_bf16_f32 v33, v38, v39
	v_cvt_pk_bf16_f32 v34, v48, v49
	v_cvt_pk_bf16_f32 v35, v52, v53
	global_store_dwordx4 v[50:51], v[32:35], off offset:256
	s_nop 1
	s_nop 0
	v_add_u32_e32 v33, 0xa0, v128
	v_mad_i64_i32 v[34:35], s[4:5], v33, s0, v[132:133]
	v_lshl_add_u64 v[34:35], v[34:35], 0, v[134:135]
	s_nop 1
	v_mov_b32_e32 v32, v241
	v_pk_mul_f32 v[30:31], v[30:31], v[32:33] op_sel_hi:[1,0]
	v_pk_mul_f32 v[28:29], v[28:29], v[32:33] op_sel_hi:[1,0]
	v_pk_mul_f32 v[26:27], v[26:27], v[32:33] op_sel_hi:[1,0]
	v_pk_mul_f32 v[24:25], v[24:25], v[32:33] op_sel_hi:[1,0]
	v_pk_mul_f32 v[22:23], v[22:23], v[32:33] op_sel_hi:[1,0]
	v_pk_mul_f32 v[20:21], v[20:21], v[32:33] op_sel_hi:[1,0]
	v_pk_mul_f32 v[36:37], v[18:19], v[32:33] op_sel_hi:[1,0]
	v_pk_mul_f32 v[32:33], v[16:17], v[32:33] op_sel_hi:[1,0]
	v_cvt_pk_bf16_f32 v16, v28, v29
	v_cvt_pk_bf16_f32 v17, v30, v31
	v_cvt_pk_bf16_f32 v18, v24, v25
	v_cvt_pk_bf16_f32 v19, v26, v27
	global_store_dwordx4 v[34:35], v[16:19], off
	s_nop 1
	v_cvt_pk_bf16_f32 v16, v20, v21
	v_cvt_pk_bf16_f32 v17, v22, v23
	v_cvt_pk_bf16_f32 v18, v32, v33
	v_cvt_pk_bf16_f32 v19, v36, v37
	global_store_dwordx4 v[34:35], v[16:19], off offset:256
	s_nop 1
	s_nop 0
	v_add_u32_e32 v17, 0xb0, v128
	v_mad_i64_i32 v[18:19], s[0:1], v17, s0, v[132:133]
	v_lshl_add_u64 v[18:19], v[18:19], 0, v[134:135]
	v_readlane_b32 s0, v235, 41
	v_readlane_b32 s1, v235, 42
	s_and_b64 vcc, exec, s[0:1]
	s_nop 1
	v_mov_b32_e32 v16, v242
	v_pk_mul_f32 v[14:15], v[14:15], v[16:17] op_sel_hi:[1,0]
	v_pk_mul_f32 v[12:13], v[12:13], v[16:17] op_sel_hi:[1,0]
	v_pk_mul_f32 v[10:11], v[10:11], v[16:17] op_sel_hi:[1,0]
	v_pk_mul_f32 v[8:9], v[8:9], v[16:17] op_sel_hi:[1,0]
	v_pk_mul_f32 v[6:7], v[6:7], v[16:17] op_sel_hi:[1,0]
	v_pk_mul_f32 v[4:5], v[4:5], v[16:17] op_sel_hi:[1,0]
	v_pk_mul_f32 v[20:21], v[2:3], v[16:17] op_sel_hi:[1,0]
	v_pk_mul_f32 v[16:17], v[0:1], v[16:17] op_sel_hi:[1,0]
	v_cvt_pk_bf16_f32 v0, v12, v13
	v_cvt_pk_bf16_f32 v1, v14, v15
	v_cvt_pk_bf16_f32 v2, v8, v9
	v_cvt_pk_bf16_f32 v3, v10, v11
	global_store_dwordx4 v[18:19], v[0:3], off
	s_nop 1
	v_cvt_pk_bf16_f32 v0, v4, v5
	v_cvt_pk_bf16_f32 v1, v6, v7
	v_cvt_pk_bf16_f32 v2, v16, v17
	v_cvt_pk_bf16_f32 v3, v20, v21
	global_store_dwordx4 v[18:19], v[0:3], off offset:256
	s_waitcnt vmcnt(0)
	s_barrier
	s_waitcnt vmcnt(0)
	s_barrier
	s_cbranch_vccnz .LBB0_2354
	v_mbcnt_lo_u32_b32 v0, -1, 0
	v_mbcnt_hi_u32_b32 v0, -1, v0
	s_nop 0
	v_cmp_eq_u32_e32 vcc, 0, v0
	s_and_saveexec_b64 s[0:1], vcc
	s_cbranch_execz .LBB0_2353
	v_mov_b32_e32 v236, 0x3400
	global_load_dword v237, v236, s[78:79] sc1
	s_mov_b64 s[6:7], exec
	buffer_wbl2 sc1
	s_waitcnt vmcnt(0)
	s_waitcnt vmcnt(0)
	s_movk_i32 s101, 0x4000
	s_branch ATD3_CHECK

ATD3_CHECK:
	v_cmp_le_u32_e32 vcc, s100, v237
	s_cbranch_vccnz ATD3_DONE
	s_sleep 2
	s_add_i32 s101, s101, -1
	s_cmp_eq_u32 s101, 0
	s_cbranch_scc0 ATD3_POLL
ATD3_DONE:
	v_mbcnt_lo_u32_b32 v0, s6, 0
	s_add_u32 s4, s78, 0x3a00
	v_mbcnt_hi_u32_b32 v0, s7, v0
	s_addc_u32 s5, s79, 0
	v_cmp_eq_u32_e32 vcc, 0, v0
	s_and_saveexec_b64 s[8:9], vcc
	s_cbranch_execz .LBB0_2344
	s_bcnt1_i32_b64 s6, s[6:7]
	v_mov_b32_e32 v0, 0
	v_mov_b32_e32 v1, s6
	global_atomic_add v0, v1, s[4:5]
